# attention unit prologue: bias-table loads left in flight while K/V DMA and Q loads are issued; LDS fill moved just before the first wait+barrier (one fewer serialized round trip per unit), on top of v
# speedup vs baseline: 1.0019x; 1.0019x over previous
.LBB0_60:
	s_ashr_i32 s11, s10, 31
	s_lshl_b32 s19, s40, 8
	s_lshl_b64 s[2:3], s[10:11], 15
	s_add_u32 s12, s30, s2
	v_mov_b32_e32 v68, v196
	s_addc_u32 s13, s31, s3
	s_add_i32 s20, s19, 0x100
	s_ashr_i32 s14, s20, 2
	v_mov_b32_e32 v16, v68
	v_readfirstlane_b32 s46, v68
	v_mov_b32_e32 v0, 0
	v_cmp_gt_i32_e32 vcc, s14, v16
	v_mov_b32_e32 v4, 0
	v_mov_b32_e32 v5, 0
	v_mov_b32_e32 v6, 0
	v_mov_b32_e32 v7, 0
	s_and_saveexec_b64 s[2:3], vcc
	s_cbranch_execz .LBB0_62
	v_ashrrev_i32_e32 v17, 31, v16
	v_lshl_add_u64 v[2:3], v[16:17], 4, s[12:13]
	global_load_dwordx4 v[238:241], v[2:3], off
.LBB0_62:
	s_or_b64 exec, exec, s[2:3]
	v_add_u32_e32 v18, 0x200, v16
	v_cmp_gt_i32_e64 s[2:3], s14, v18
	v_mov_b32_e32 v1, 0
	v_mov_b32_e32 v2, 0
	v_mov_b32_e32 v3, 0
	s_and_saveexec_b64 s[4:5], s[2:3]
	s_cbranch_execz .LBB0_64
	v_ashrrev_i32_e32 v19, 31, v18
	v_lshl_add_u64 v[0:1], v[18:19], 4, s[12:13]
	global_load_dwordx4 v[242:245], v[0:1], off
.LBB0_64:
	s_or_b64 exec, exec, s[4:5]
	v_add_u32_e32 v20, 0x400, v16
	v_cmp_gt_i32_e64 s[4:5], s14, v20
	v_mov_b32_e32 v8, 0
	v_mov_b32_e32 v12, 0
	v_mov_b32_e32 v13, 0
	v_mov_b32_e32 v14, 0
	v_mov_b32_e32 v15, 0
	s_and_saveexec_b64 s[6:7], s[4:5]
	s_cbranch_execz .LBB0_66
	v_ashrrev_i32_e32 v21, 31, v20
	v_lshl_add_u64 v[10:11], v[20:21], 4, s[12:13]
	global_load_dwordx4 v[246:249], v[10:11], off
.LBB0_66:
	s_or_b64 exec, exec, s[6:7]
	v_add_u32_e32 v22, 0x600, v16
	v_cmp_gt_i32_e64 s[6:7], s14, v22
	s_mov_b64 s[56:57], vcc
	s_mov_b64 s[80:81], s[2:3]
	s_mov_b64 s[86:87], s[4:5]
	s_mov_b64 s[90:91], s[6:7]
	v_mov_b32_e32 v9, 0
	v_mov_b32_e32 v10, 0
	v_mov_b32_e32 v11, 0
	s_and_saveexec_b64 s[14:15], s[6:7]
	s_cbranch_execnz .LBB0_91
	s_or_b64 exec, exec, s[14:15]
	s_and_saveexec_b64 s[12:13], vcc
	s_cbranch_execnz .LBB0_92

.LBB0_70:
.LBB0_71:
	s_or_b64 exec, exec, s[2:3]
	s_lshr_b32 s2, s11, 28
	s_add_i32 s3, s10, s2
	s_ashr_i32 s2, s3, 4
	s_and_b32 s3, s3, -16
	s_sub_i32 s12, s10, s3
	s_and_saveexec_b64 s[4:5], s[6:7]
	s_cbranch_execz .LBB0_73
.LBB0_73:
	s_or_b64 exec, exec, s[4:5]
	s_ashr_i32 s3, s2, 31
	s_ashr_i32 s11, s46, 6
	s_lshl_b64 s[4:5], s[2:3], 13
	s_ashr_i32 s6, s19, 31
	s_add_u32 s4, s4, s19
	s_addc_u32 s5, s5, s6
	s_lshl_b32 s21, s11, 5
	s_ashr_i32 s7, s21, 31
	s_add_u32 s6, s4, s21
	s_addc_u32 s7, s5, s7
	s_lshl_b32 s12, s12, 6
	s_ashr_i32 s13, s12, 31
	s_lshl_b64 s[4:5], s[2:3], 24
	s_add_u32 s14, s27, s4
	s_addc_u32 s15, s29, s5
	s_lshl_b64 s[2:3], s[6:7], 11
	s_add_u32 s2, s23, s2
	s_addc_u32 s3, s24, s3
	s_lshl_b64 s[12:13], s[12:13], 1
	s_add_u32 s6, s2, s12
	s_addc_u32 s7, s3, s13
	s_add_u32 s2, s14, s12
	s_addc_u32 s3, s15, s13
	s_add_u32 s14, s25, s4
	s_addc_u32 s15, s26, s5
	v_and_b32_e32 v193, 63, v68
	s_add_u32 s14, s14, s12
	s_addc_u32 s15, s15, s13
	v_lshlrev_b32_e32 v180, 11, v193
	v_mov_b32_e32 v181, v99
	v_lshl_add_u64 v[0:1], s[14:15], 0, v[180:181]
	s_lshl_b32 s14, s11, 3
	s_ashr_i32 s15, s14, 31
	s_lshl_b32 s16, s11, 4
	v_bfe_u32 v188, v68, 2, 4
	v_lshl_add_u64 v[64:65], s[14:15], 1, v[0:1]
	v_and_or_b32 v0, s16, 48, v188
	v_lshlrev_b32_e32 v98, 11, v0
	v_lshl_add_u64 v[0:1], s[2:3], 0, v[98:99]
	s_ashr_i32 s2, s46, 3
	s_and_b32 s16, s2, 0xffffffe0
	s_ashr_i32 s17, s16, 31
	s_lshl_b32 s18, s11, 10
	v_lshlrev_b32_e32 v2, 3, v68
	s_cmp_lg_u32 0, -1
	s_waitcnt lgkmcnt(0)
	v_and_b32_e32 v224, 24, v2
	s_cselect_b32 s2, 0, 0
	v_lshl_add_u64 v[0:1], s[16:17], 1, v[0:1]
	v_lshlrev_b32_e32 v98, 1, v224
	s_add_i32 s42, s18, s2
	s_mov_b32 s2, m0
	s_mov_b32 m0, s42
	s_nop 0
	global_load_lds_dwordx4 v[64:65], off
	s_mov_b32 m0, s2
	v_lshl_add_u64 v[66:67], v[0:1], 0, v[98:99]
	s_add_i32 s43, s42, 0x6000
	s_mov_b32 s2, m0
	s_mov_b32 m0, s43
	s_nop 0
	global_load_lds_dwordx4 v[66:67], off
	s_mov_b32 m0, s2
	s_mov_b64 s[2:3], 0x20000
	v_and_b32_e32 v197, 31, v68
	v_lshl_add_u64 v[0:1], v[64:65], 0, s[2:3]
	v_bfe_u32 v223, v68, 5, 1
	s_add_i32 s2, s42, 0x2000
	s_mov_b32 s3, m0
	s_mov_b32 m0, s2
	s_nop 0
	global_load_lds_dwordx4 v[0:1], off
	s_mov_b32 m0, s3
	v_lshlrev_b32_e32 v0, 11, v197
	v_lshl_or_b32 v98, v223, 4, v0
	v_lshl_add_u64 v[0:1], s[6:7], 0, v[98:99]
	flat_load_dwordx4 v[132:135], v[0:1]
	flat_load_dwordx4 v[124:127], v[0:1] offset:32
	flat_load_dwordx4 v[116:119], v[0:1] offset:64
	flat_load_dwordx4 v[108:111], v[0:1] offset:96
	s_add_i32 s2, s42, 0x4000
	v_lshl_add_u64 v[0:1], v[64:65], 0, s[68:69]
	s_mov_b32 s3, m0
	s_mov_b32 m0, s2
	s_nop 0
	global_load_lds_dwordx4 v[0:1], off
	s_mov_b32 m0, s3
	v_lshl_add_u32 v44, v197, 2, 0
	s_waitcnt vmcnt(8)
	s_and_saveexec_b64 s[96:97], s[56:57]
	s_cbranch_execz .Lab0
	v_lshl_add_u32 v0, v68, 4, 0
	v_add_u32_e32 v0, 0x14800, v0
	ds_write_b128 v0, v[238:241]
.Lab0:
	s_or_b64 exec, exec, s[96:97]
	s_and_saveexec_b64 s[96:97], s[80:81]
	s_cbranch_execz .Lab1
	v_add_u32_e32 v0, 0x200, v68
	v_lshl_add_u32 v0, v0, 4, 0
	v_add_u32_e32 v0, 0x14800, v0
	ds_write_b128 v0, v[242:245]
.Lab1:
	s_or_b64 exec, exec, s[96:97]
	s_and_saveexec_b64 s[96:97], s[86:87]
	s_cbranch_execz .Lab2
	v_add_u32_e32 v0, 0x400, v68
	v_lshl_add_u32 v0, v0, 4, 0
	v_add_u32_e32 v0, 0x14800, v0
	ds_write_b128 v0, v[246:249]
.Lab2:
	s_or_b64 exec, exec, s[96:97]
	s_and_saveexec_b64 s[96:97], s[90:91]
	s_cbranch_execz .Lab3
	v_add_u32_e32 v0, 0x600, v68
	v_lshl_add_u32 v0, v0, 4, 0
	v_add_u32_e32 v0, 0x14800, v0
	ds_write_b128 v0, v[250:253]
.Lab3:
	s_or_b64 exec, exec, s[96:97]
	s_waitcnt vmcnt(3) lgkmcnt(0)
	s_barrier
	v_add_u32_e32 v0, 0x14800, v44
	ds_read2_b32 v[0:1], v0 offset1:32
	v_cmp_gt_u32_e64 s[2:3], 32, v193
	v_mov_b32_e32 v103, v99
	v_mov_b32_e32 v102, s53
	v_cndmask_b32_e64 v100, 0, v211, s[2:3]
	s_waitcnt lgkmcnt(0)
	v_and_b32_e32 v2, 0xffff0000, v0
	v_sub_f32_e32 v2, v0, v2
	v_and_b32_e32 v3, 0xffff0000, v2
	v_sub_f32_e32 v2, v2, v3
	v_or_b32_sdwa v0, v3, v0 dst_sel:DWORD dst_unused:UNUSED_PAD src0_sel:DWORD src1_sel:WORD_1
	v_cndmask_b32_e64 v96, 0, v0, s[2:3]
	v_or_b32_sdwa v0, v2, v209 dst_sel:DWORD dst_unused:UNUSED_PAD src0_sel:WORD_1 src1_sel:DWORD
	v_cndmask_b32_e64 v97, 0, v0, s[2:3]
	v_and_b32_e32 v0, 0xffff0000, v1
	v_sub_f32_e32 v0, v1, v0
	v_and_b32_e32 v2, 0xffff0000, v0
	v_sub_f32_e32 v0, v0, v2
	v_or_b32_sdwa v1, v2, v1 dst_sel:DWORD dst_unused:UNUSED_PAD src0_sel:DWORD src1_sel:WORD_1
	v_or_b32_sdwa v0, v0, v209 dst_sel:DWORD dst_unused:UNUSED_PAD src0_sel:WORD_1 src1_sel:DWORD
	v_cndmask_b32_e64 v101, 0, v212, s[2:3]
	v_cndmask_b32_e64 v98, 0, v210, s[2:3]
	v_cndmask_b32_e64 v16, 0, v1, s[2:3]
	v_cndmask_b32_e64 v17, 0, v0, s[2:3]
	v_mov_b64_e32 v[0:1], v[96:97]
	v_mov_b64_e32 v[20:21], v[100:101]
	v_mov_b32_e32 v18, v98
	v_mov_b32_e32 v19, v99
	v_mov_b64_e32 v[2:3], v[98:99]
	v_mov_b64_e32 v[22:23], v[102:103]
	v_lshlrev_b32_e32 v24, 10, v223
	v_lshlrev_b32_e32 v25, 4, v197
	v_mfma_f32_32x32x16_bf16 v[0:15], v[0:3], v[20:23], 0
	v_add3_u32 v230, 0, v24, v25
	ds_read_b128 v[32:35], v230
	ds_read_b128 v[36:39], v230 offset:512
	s_ashr_i32 s44, s20, 6
	v_or_b32_e32 v228, s21, v197
	s_cmp_gt_i32 s44, 4
	v_lshlrev_b32_e32 v226, 2, v223
	v_mfma_f32_32x32x16_bf16 v[16:31], v[16:19], v[20:23], 0
	s_waitcnt vmcnt(0) lgkmcnt(0)
	v_mfma_f32_32x32x16_bf16 v[0:15], v[32:35], v[132:135], v[0:15]
	v_mfma_f32_32x32x16_bf16 v[16:31], v[36:39], v[132:135], v[16:31]
	ds_read_b128 v[32:35], v230 offset:2048
	ds_read_b128 v[36:39], v230 offset:2560
	s_waitcnt lgkmcnt(1)
	v_mfma_f32_32x32x16_bf16 v[0:15], v[32:35], v[124:127], v[0:15]
	s_waitcnt lgkmcnt(0)
	v_mfma_f32_32x32x16_bf16 v[16:31], v[36:39], v[124:127], v[16:31]
	ds_read_b128 v[32:35], v230 offset:4096
	ds_read_b128 v[36:39], v230 offset:4608
	s_waitcnt lgkmcnt(1)
	v_mfma_f32_32x32x16_bf16 v[0:15], v[32:35], v[116:119], v[0:15]
	s_waitcnt lgkmcnt(0)
	v_mfma_f32_32x32x16_bf16 v[16:31], v[36:39], v[116:119], v[16:31]
	ds_read_b128 v[32:35], v230 offset:6144
	ds_read_b128 v[36:39], v230 offset:6656
	s_waitcnt lgkmcnt(1)
	v_mfma_f32_32x32x16_bf16 v[0:15], v[32:35], v[108:111], v[0:15]
	s_waitcnt lgkmcnt(0)
	v_mfma_f32_32x32x16_bf16 v[16:31], v[36:39], v[108:111], v[16:31]
	s_nop 15
	s_nop 7
	s_cbranch_scc1 .LBB0_75
	v_subrev_u32_e32 v32, s19, v226
	v_or_b32_e32 v33, 32, v32
	v_cmp_le_i32_e32 vcc, v33, v228
	v_or_b32_e32 v33, 33, v32
	s_nop 6
	v_cndmask_b32_e32 v16, v213, v16, vcc
	v_cmp_lt_i32_e32 vcc, v32, v228
	s_nop 1
	v_cndmask_b32_e32 v1, v213, v1, vcc
	v_cmp_le_i32_e32 vcc, v32, v228
	s_nop 1
	v_cndmask_b32_e32 v0, v213, v0, vcc
	v_cmp_le_i32_e32 vcc, v33, v228
	v_or_b32_e32 v33, 2, v32
	s_nop 0
	v_cndmask_b32_e32 v17, v213, v17, vcc
	v_cmp_le_i32_e32 vcc, v33, v228
	v_or_b32_e32 v33, 34, v32
	s_nop 0
	v_cndmask_b32_e32 v2, v213, v2, vcc
	v_cmp_le_i32_e32 vcc, v33, v228
	v_or_b32_e32 v33, 3, v32
	s_nop 0
	v_cndmask_b32_e32 v18, v213, v18, vcc
	v_cmp_le_i32_e32 vcc, v33, v228
	v_or_b32_e32 v33, 35, v32
	s_nop 0
	v_cndmask_b32_e32 v3, v213, v3, vcc
	v_cmp_le_i32_e32 vcc, v33, v228
	v_or_b32_e32 v33, 8, v32
	s_nop 0
	v_cndmask_b32_e32 v19, v213, v19, vcc
	v_cmp_le_i32_e32 vcc, v33, v228
	v_or_b32_e32 v33, 40, v32
	s_nop 0
	v_cndmask_b32_e32 v4, v213, v4, vcc
	v_cmp_le_i32_e32 vcc, v33, v228
	v_or_b32_e32 v33, 9, v32
	s_nop 0
	v_cndmask_b32_e32 v20, v213, v20, vcc
	v_cmp_le_i32_e32 vcc, v33, v228
	v_or_b32_e32 v33, 41, v32
	s_nop 0
	v_cndmask_b32_e32 v5, v213, v5, vcc
	v_cmp_le_i32_e32 vcc, v33, v228
	v_or_b32_e32 v33, 10, v32
	s_nop 0
	v_cndmask_b32_e32 v21, v213, v21, vcc
	v_cmp_le_i32_e32 vcc, v33, v228
	v_or_b32_e32 v33, 42, v32
	s_nop 0
	v_cndmask_b32_e32 v6, v213, v6, vcc
	v_cmp_le_i32_e32 vcc, v33, v228
	v_or_b32_e32 v33, 11, v32
	s_nop 0
	v_cndmask_b32_e32 v22, v213, v22, vcc
	v_cmp_le_i32_e32 vcc, v33, v228
	v_or_b32_e32 v33, 43, v32
	s_nop 0
	v_cndmask_b32_e32 v7, v213, v7, vcc
	v_cmp_le_i32_e32 vcc, v33, v228
	v_or_b32_e32 v33, 16, v32
	s_nop 0
	v_cndmask_b32_e32 v23, v213, v23, vcc
	v_cmp_le_i32_e32 vcc, v33, v228
	v_or_b32_e32 v33, 48, v32
	s_nop 0
	v_cndmask_b32_e32 v8, v213, v8, vcc
	v_cmp_le_i32_e32 vcc, v33, v228
	v_or_b32_e32 v33, 17, v32
	s_nop 0
	v_cndmask_b32_e32 v24, v213, v24, vcc
	v_cmp_le_i32_e32 vcc, v33, v228
	v_or_b32_e32 v33, 49, v32
	s_nop 0
	v_cndmask_b32_e32 v9, v213, v9, vcc
	v_cmp_le_i32_e32 vcc, v33, v228
	v_or_b32_e32 v33, 18, v32
	s_nop 0
	v_cndmask_b32_e32 v25, v213, v25, vcc
	v_cmp_le_i32_e32 vcc, v33, v228
	v_or_b32_e32 v33, 50, v32
	s_nop 0
	v_cndmask_b32_e32 v10, v213, v10, vcc
	v_cmp_le_i32_e32 vcc, v33, v228
	v_or_b32_e32 v33, 19, v32
	s_nop 0
	v_cndmask_b32_e32 v26, v213, v26, vcc
	v_cmp_le_i32_e32 vcc, v33, v228
	v_or_b32_e32 v33, 51, v32
	s_nop 0
	v_cndmask_b32_e32 v11, v213, v11, vcc
	v_cmp_le_i32_e32 vcc, v33, v228
	v_or_b32_e32 v33, 24, v32
	s_nop 0
	v_cndmask_b32_e32 v27, v213, v27, vcc
	v_cmp_le_i32_e32 vcc, v33, v228
	v_or_b32_e32 v33, 56, v32
	s_nop 0
	v_cndmask_b32_e32 v12, v213, v12, vcc
	v_cmp_le_i32_e32 vcc, v33, v228
	v_or_b32_e32 v33, 25, v32
	s_nop 0
	v_cndmask_b32_e32 v28, v213, v28, vcc
	v_cmp_le_i32_e32 vcc, v33, v228
	v_or_b32_e32 v33, 57, v32
	s_nop 0
	v_cndmask_b32_e32 v13, v213, v13, vcc
	v_cmp_le_i32_e32 vcc, v33, v228
	v_or_b32_e32 v33, 26, v32
	s_nop 0
	v_cndmask_b32_e32 v29, v213, v29, vcc
	v_cmp_le_i32_e32 vcc, v33, v228
	v_or_b32_e32 v33, 58, v32
	s_nop 0
	v_cndmask_b32_e32 v14, v213, v14, vcc
	v_cmp_le_i32_e32 vcc, v33, v228
	v_or_b32_e32 v33, 27, v32
	v_or_b32_e32 v32, 59, v32
	v_cndmask_b32_e32 v30, v213, v30, vcc
	v_cmp_le_i32_e32 vcc, v33, v228
	s_nop 1
	v_cndmask_b32_e32 v15, v213, v15, vcc
	v_cmp_le_i32_e32 vcc, v32, v228
	s_nop 1
	v_cndmask_b32_e32 v31, v213, v31, vcc

.LBB0_91:
	v_ashrrev_i32_e32 v23, 31, v22
	v_lshl_add_u64 v[8:9], v[22:23], 4, s[12:13]
	global_load_dwordx4 v[250:253], v[8:9], off
	s_or_b64 exec, exec, s[14:15]
	s_and_saveexec_b64 s[12:13], vcc
	s_cbranch_execz .LBB0_68
.LBB0_92:
	s_or_b64 exec, exec, s[12:13]
	s_and_saveexec_b64 s[12:13], s[2:3]
	s_cbranch_execz .LBB0_69
.LBB0_93:
	s_or_b64 exec, exec, s[12:13]
	s_and_saveexec_b64 s[2:3], s[4:5]
	s_cbranch_execnz .LBB0_70
	s_branch .LBB0_71
